# attention: K/V tile it+1 staged into LDS in the middle of tile it's PV block (write-ahead) instead of at the top of tile it+1
# baseline (speedup 1.0000x reference)
.LBB0_1727:
	v_cndmask_b32_e64 v194, v168, v181, s[0:1]
	v_sub_f32_e32 v80, v80, v194
	v_exp_f32_e32 v186, v80
	v_sub_f32_e32 v80, v82, v194
	v_exp_f32_e32 v196, v80
	v_sub_f32_e32 v80, v83, v194
	v_exp_f32_e32 v197, v80
	v_sub_f32_e32 v80, v84, v194
	v_sub_f32_e32 v64, v64, v194
	v_exp_f32_e32 v198, v80
	v_sub_f32_e32 v80, v85, v194
	v_add3_u32 v200, s15, v171, v144
	v_exp_f32_e32 v195, v64
	v_sub_f32_e32 v64, v81, v194
	v_exp_f32_e32 v199, v80
	ds_read_b128 v[80:83], v200 offset:34816
	ds_read_b128 v[182:185], v200 offset:34848
	v_sub_f32_e32 v84, v86, v194
	v_exp_f32_e32 v201, v84
	v_sub_f32_e32 v84, v87, v194
	v_exp_f32_e32 v64, v64
	v_exp_f32_e32 v202, v84
	v_cvt_pk_bf16_f32 v85, v196, v197
	v_cvt_pk_bf16_f32 v86, v198, v199
	v_cvt_pk_bf16_f32 v84, v186, v64
	v_cvt_pk_bf16_f32 v87, v201, v202
	v_sub_f32_e32 v88, v88, v194
	v_add_f32_e32 v203, v186, v195
	s_waitcnt lgkmcnt(1)
	v_mfma_f32_32x32x16_bf16 v[48:63], v[80:83], v[84:87], v[48:63]
	ds_read_b128 v[80:83], v200 offset:39424
	v_exp_f32_e32 v204, v88
	ds_read_b128 v[186:189], v200 offset:44032
	ds_read_b128 v[190:193], v200 offset:39456
	v_sub_f32_e32 v207, v91, v194
	v_sub_f32_e32 v65, v65, v194
	v_sub_f32_e32 v92, v92, v194
	v_sub_f32_e32 v93, v93, v194
	s_waitcnt lgkmcnt(2)
	v_mfma_f32_32x32x16_bf16 v[32:47], v[80:83], v[84:87], v[32:47]
	v_sub_f32_e32 v80, v89, v194
	v_exp_f32_e32 v205, v80
	v_sub_f32_e32 v80, v90, v194
	v_exp_f32_e32 v206, v80
	ds_read_b128 v[80:83], v200 offset:48640
	ds_read_b128 v[88:91], v200 offset:44064
	v_sub_f32_e32 v94, v94, v194
	v_exp_f32_e32 v207, v207
	s_waitcnt lgkmcnt(3)
	v_mfma_f32_32x32x16_bf16 v[16:31], v[186:189], v[84:87], v[16:31]
	v_exp_f32_e32 v92, v92
	v_exp_f32_e32 v93, v93
	v_exp_f32_e32 v94, v94
	ds_read_b128 v[186:189], v200 offset:48672
	v_sub_f32_e32 v78, v78, v194
	s_waitcnt lgkmcnt(2)
	v_mfma_f32_32x32x16_bf16 v[0:15], v[80:83], v[84:87], v[0:15]
	v_exp_f32_e32 v84, v65
	v_sub_f32_e32 v65, v66, v194
	v_exp_f32_e32 v85, v65
	v_sub_f32_e32 v80, v95, v194
	v_sub_f32_e32 v66, v67, v194
	v_exp_f32_e32 v95, v80
	v_exp_f32_e32 v86, v66
	v_add_f32_e32 v65, 0, v203
	v_add_f32_e32 v64, v64, v84
	v_add_f32_e32 v64, v64, v65
	v_add_f32_e32 v65, v196, v85
	v_add_f32_e32 v64, v65, v64
	v_sub_f32_e32 v65, v68, v194
	v_cvt_pk_bf16_f32 v80, v204, v205
	v_cvt_pk_bf16_f32 v81, v206, v207
	v_cvt_pk_bf16_f32 v82, v92, v93
	v_cvt_pk_bf16_f32 v83, v94, v95
	v_exp_f32_e32 v87, v65
	v_add_f32_e32 v65, v197, v86
	v_mfma_f32_32x32x16_bf16 v[48:63], v[182:185], v[80:83], v[48:63]
	v_add_f32_e32 v182, v65, v64
	v_sub_f32_e32 v64, v69, v194
	v_sub_f32_e32 v68, v71, v194
	v_exp_f32_e32 v184, v68
	v_cvt_pk_bf16_f32 v68, v195, v84
	v_cvt_pk_bf16_f32 v69, v85, v86
	s_waitcnt lgkmcnt(1)
	v_mfma_f32_32x32x16_bf16 v[16:31], v[88:91], v[80:83], v[16:31]
	v_exp_f32_e32 v89, v64
	v_sub_f32_e32 v64, v70, v194
	v_exp_f32_e32 v183, v64
	ds_read_b128 v[64:67], v200 offset:34880
	v_add_f32_e32 v88, v198, v87
	v_cvt_pk_bf16_f32 v70, v87, v89
	v_cvt_pk_bf16_f32 v71, v183, v184
	v_mfma_f32_32x32x16_bf16 v[32:47], v[190:193], v[80:83], v[32:47]
	s_waitcnt lgkmcnt(0)
	v_mfma_f32_32x32x16_bf16 v[48:63], v[64:67], v[68:71], v[48:63]
	v_add3_u32 v208, s32, v179, v177
	s_waitcnt vmcnt(3)
	ds_write_b128 v208, v[100:103]
	v_add3_u32 v208, s32, v180, v177
	s_waitcnt vmcnt(2)
	ds_write_b128 v208, v[96:99]
	v_add3_u32 v208, s94, v176, v178
	s_waitcnt vmcnt(1)
	ds_write_b128 v208, v[104:107] offset:34816
	s_waitcnt vmcnt(0)
	ds_write_b128 v208, v[108:111] offset:44032
	s_mov_b32 s32, -1
	v_add_f32_e32 v64, v88, v182
	v_add_f32_e32 v65, v199, v89
	v_add_f32_e32 v182, v65, v64
	v_sub_f32_e32 v64, v72, v194
	v_exp_f32_e32 v185, v64
	v_sub_f32_e32 v72, v73, v194
	v_mfma_f32_32x32x16_bf16 v[0:15], v[186:189], v[80:83], v[0:15]
	ds_read_b128 v[80:83], v200 offset:39488
	ds_read_b128 v[84:87], v200 offset:34912
	ds_read_b128 v[64:67], v200 offset:44096
	ds_read_b128 v[88:91], v200 offset:39520
	v_exp_f32_e32 v186, v72
	v_sub_f32_e32 v72, v74, v194
	v_exp_f32_e32 v187, v72
	v_sub_f32_e32 v188, v75, v194
	v_exp_f32_e32 v188, v188
	s_waitcnt lgkmcnt(3)
	v_mfma_f32_32x32x16_bf16 v[32:47], v[80:83], v[68:71], v[32:47]
	ds_read_b128 v[72:75], v200 offset:48704
	ds_read_b128 v[80:83], v200 offset:44128
	s_waitcnt lgkmcnt(3)
	v_mfma_f32_32x32x16_bf16 v[16:31], v[64:67], v[68:71], v[16:31]
	v_sub_f32_e32 v64, v76, v194
	v_exp_f32_e32 v76, v64
	v_sub_f32_e32 v64, v77, v194
	v_exp_f32_e32 v77, v64
	ds_read_b128 v[64:67], v200 offset:48736
	s_waitcnt lgkmcnt(2)
	v_mfma_f32_32x32x16_bf16 v[0:15], v[72:75], v[68:71], v[0:15]
	v_sub_f32_e32 v68, v79, v194
	v_exp_f32_e32 v72, v78
	v_exp_f32_e32 v73, v68
	v_add_f32_e32 v74, v201, v183
	v_add_f32_e32 v74, v74, v182
	v_add_f32_e32 v75, v202, v184
	v_add_f32_e32 v74, v75, v74
	v_add_f32_e32 v75, v204, v185
	v_add_f32_e32 v74, v75, v74
	v_add_f32_e32 v75, v205, v186
	v_cvt_pk_bf16_f32 v68, v185, v186
	v_cvt_pk_bf16_f32 v69, v187, v188
	v_cvt_pk_bf16_f32 v70, v76, v77
	v_cvt_pk_bf16_f32 v71, v72, v73
	v_add_f32_e32 v74, v75, v74
	v_add_f32_e32 v75, v206, v187
	v_mfma_f32_32x32x16_bf16 v[48:63], v[84:87], v[68:71], v[48:63]
	v_add_f32_e32 v74, v75, v74
	v_add_f32_e32 v75, v207, v188
	v_add_f32_e32 v74, v75, v74
	v_add_f32_e32 v75, v92, v76
	v_add_f32_e32 v74, v75, v74
	v_add_f32_e32 v75, v93, v77
	v_add_f32_e32 v74, v75, v74
	v_mfma_f32_32x32x16_bf16 v[32:47], v[88:91], v[68:71], v[32:47]
	v_add_f32_e32 v72, v94, v72
	v_add_f32_e32 v72, v72, v74
	v_add_f32_e32 v73, v95, v73
	v_add_f32_e32 v72, v73, v72
	v_fmac_f32_e32 v72, v170, v154
	v_mov_b32_e32 v154, v181
	v_mov_b32_e32 v170, v72
	s_waitcnt lgkmcnt(1)
	v_mfma_f32_32x32x16_bf16 v[16:31], v[80:83], v[68:71], v[16:31]
	s_waitcnt lgkmcnt(0)
	v_mfma_f32_32x32x16_bf16 v[0:15], v[64:67], v[68:71], v[0:15]
.LBB0_1728:
	s_or_b64 exec, exec, s[4:5]
	s_cmp_eq_u32 s32, -1
	s_cbranch_scc0 .Lattn_u1_latewrite
.Lattn_u1_latedone:
	s_add_u32 s98, s98, 0x4000
	s_addc_u32 s99, s99, 0
	s_add_u32 s100, s100, 0x4000
	s_addc_u32 s101, s101, 0
	s_add_u32 s44, s44, 0x80
	s_addc_u32 s45, s45, 0
	s_add_u32 s46, s46, 0x80
	s_addc_u32 s47, s47, 0
	s_add_i32 s84, s84, 1
	s_cmp_eq_u32 s14, s84
	s_cbranch_scc1 .LBB0_1740
.LBB0_1729:
	s_and_b32 s0, s84, 1
	s_mul_i32 s1, s0, 0x4400
	s_add_i32 s16, s1, 0
	s_lshl_b32 s0, s0, 10
	s_add_i32 s15, s16, s0
	s_sub_i32 s32, 0x4400, s16
	s_sub_i32 s94, 0x400, s0
	s_add_i32 s94, s94, s32
	s_cmp_lg_u32 s84, 0
	s_cbranch_scc1 .Lattn_u1_nowrite
	v_add3_u32 v64, s16, v179, v177
	s_waitcnt vmcnt(3)
	ds_write_b128 v64, v[100:103]
	v_add3_u32 v64, s16, v180, v177
	s_waitcnt vmcnt(2)
	ds_write_b128 v64, v[96:99]
	v_add3_u32 v64, s15, v176, v178
	s_waitcnt vmcnt(1)
	ds_write_b128 v64, v[104:107] offset:34816
	s_waitcnt vmcnt(0)
	ds_write_b128 v64, v[108:111] offset:44032
.Lattn_u1_nowrite:
	v_lshl_add_u64 v[66:67], v[152:153], 0, s[98:99]
	v_lshl_add_u64 v[64:65], v[152:153], 0, s[100:101]
	s_waitcnt lgkmcnt(0)
	s_barrier
	global_load_dwordx4 v[100:103], v[66:67], off
	global_load_dwordx4 v[96:99], v[64:65], off
	v_lshl_add_u64 v[66:67], v[150:151], 0, s[44:45]
	s_lshr_b32 s0, s84, 2
	v_lshl_add_u64 v[64:65], v[150:151], 0, s[46:47]
	s_cmp_eq_u32 s0, s81
	global_load_dwordx4 v[104:107], v[66:67], off offset:128
	global_load_dwordx4 v[108:111], v[64:65], off offset:128
	s_cselect_b64 s[8:9], -1, 0
	s_lshl_b32 s1, 1, s0
	v_and_b32_e32 v64, s1, v173
	s_cmp_lg_u32 s0, s81
	v_cmp_ne_u32_e64 s[0:1], 0, v64
	s_mov_b64 s[4:5], -1
	s_cbranch_scc0 .LBB0_1732
	v_cndmask_b32_e64 v64, 0, 1, s[0:1]
	v_cmp_ne_u32_e32 vcc, 0, v64
	s_cmp_lg_u64 vcc, 0
	s_cselect_b64 s[10:11], -1, 0
	s_and_b32 s17, s84, 3
	s_cbranch_execz .LBB0_1733

.Lattn_u1_latewrite:
	v_add3_u32 v208, s32, v179, v177
	s_waitcnt vmcnt(3)
	ds_write_b128 v208, v[100:103]
	v_add3_u32 v208, s32, v180, v177
	s_waitcnt vmcnt(2)
	ds_write_b128 v208, v[96:99]
	v_add3_u32 v208, s94, v176, v178
	s_waitcnt vmcnt(1)
	ds_write_b128 v208, v[104:107] offset:34816
	s_waitcnt vmcnt(0)
	ds_write_b128 v208, v[108:111] offset:44032
	s_branch .Lattn_u1_latedone
.LBB0_1740:
	s_and_b32 s0, s14, 1
	s_mul_i32 s1, s0, 0x4400
	s_add_i32 s16, s1, 0
	s_lshl_b32 s0, s0, 10
	s_add_i32 s15, s16, s0
	s_lshr_b32 s0, s14, 2
	s_cmp_eq_u32 s0, s81
	v_lshrrev_b32_e32 v64, s0, v173
	s_cselect_b64 s[8:9], -1, 0
	v_and_b32_e32 v64, 1, v64
	v_cmp_eq_u32_e64 s[0:1], 1, v64
	s_mov_b64 s[4:5], -1
	s_and_b64 vcc, exec, s[8:9]
	s_waitcnt lgkmcnt(0)
	s_barrier
	s_cbranch_vccnz .LBB0_1743
	v_cndmask_b32_e64 v64, 0, 1, s[0:1]
	v_cmp_ne_u32_e32 vcc, 0, v64
	s_cmp_lg_u64 vcc, 0
	s_cselect_b64 s[10:11], -1, 0
	s_and_b32 s14, s14, 3
	s_cbranch_execz .LBB0_1744

.LBB0_1770:
	v_cndmask_b32_e64 v194, v168, v181, s[0:1]
	v_sub_f32_e32 v80, v80, v194
	v_exp_f32_e32 v186, v80
	v_sub_f32_e32 v80, v82, v194
	v_exp_f32_e32 v196, v80
	v_sub_f32_e32 v80, v83, v194
	v_exp_f32_e32 v197, v80
	v_sub_f32_e32 v80, v84, v194
	v_sub_f32_e32 v64, v64, v194
	v_exp_f32_e32 v198, v80
	v_sub_f32_e32 v80, v85, v194
	v_add3_u32 v200, s16, v171, v144
	v_exp_f32_e32 v195, v64
	v_sub_f32_e32 v64, v81, v194
	v_exp_f32_e32 v199, v80
	ds_read_b128 v[80:83], v200 offset:34816
	ds_read_b128 v[182:185], v200 offset:34848
	v_sub_f32_e32 v84, v86, v194
	v_exp_f32_e32 v201, v84
	v_sub_f32_e32 v84, v87, v194
	v_exp_f32_e32 v64, v64
	v_exp_f32_e32 v202, v84
	v_cvt_pk_bf16_f32 v85, v196, v197
	v_cvt_pk_bf16_f32 v86, v198, v199
	v_cvt_pk_bf16_f32 v84, v186, v64
	v_cvt_pk_bf16_f32 v87, v201, v202
	v_sub_f32_e32 v88, v88, v194
	v_add_f32_e32 v203, v186, v195
	s_waitcnt lgkmcnt(1)
	v_mfma_f32_32x32x16_bf16 v[48:63], v[80:83], v[84:87], v[48:63]
	ds_read_b128 v[80:83], v200 offset:39424
	v_exp_f32_e32 v204, v88
	ds_read_b128 v[186:189], v200 offset:44032
	ds_read_b128 v[190:193], v200 offset:39456
	v_sub_f32_e32 v207, v91, v194
	v_sub_f32_e32 v65, v65, v194
	v_sub_f32_e32 v92, v92, v194
	v_sub_f32_e32 v93, v93, v194
	s_waitcnt lgkmcnt(2)
	v_mfma_f32_32x32x16_bf16 v[32:47], v[80:83], v[84:87], v[32:47]
	v_sub_f32_e32 v80, v89, v194
	v_exp_f32_e32 v205, v80
	v_sub_f32_e32 v80, v90, v194
	v_exp_f32_e32 v206, v80
	ds_read_b128 v[80:83], v200 offset:48640
	ds_read_b128 v[88:91], v200 offset:44064
	v_sub_f32_e32 v94, v94, v194
	v_exp_f32_e32 v207, v207
	s_waitcnt lgkmcnt(3)
	v_mfma_f32_32x32x16_bf16 v[16:31], v[186:189], v[84:87], v[16:31]
	v_exp_f32_e32 v92, v92
	v_exp_f32_e32 v93, v93
	v_exp_f32_e32 v94, v94
	ds_read_b128 v[186:189], v200 offset:48672
	v_sub_f32_e32 v78, v78, v194
	s_waitcnt lgkmcnt(2)
	v_mfma_f32_32x32x16_bf16 v[0:15], v[80:83], v[84:87], v[0:15]
	v_exp_f32_e32 v84, v65
	v_sub_f32_e32 v65, v66, v194
	v_exp_f32_e32 v85, v65
	v_sub_f32_e32 v80, v95, v194
	v_sub_f32_e32 v66, v67, v194
	v_exp_f32_e32 v95, v80
	v_exp_f32_e32 v86, v66
	v_add_f32_e32 v65, 0, v203
	v_add_f32_e32 v64, v64, v84
	v_add_f32_e32 v64, v64, v65
	v_add_f32_e32 v65, v196, v85
	v_add_f32_e32 v64, v65, v64
	v_sub_f32_e32 v65, v68, v194
	v_cvt_pk_bf16_f32 v80, v204, v205
	v_cvt_pk_bf16_f32 v81, v206, v207
	v_cvt_pk_bf16_f32 v82, v92, v93
	v_cvt_pk_bf16_f32 v83, v94, v95
	v_exp_f32_e32 v87, v65
	v_add_f32_e32 v65, v197, v86
	v_mfma_f32_32x32x16_bf16 v[48:63], v[182:185], v[80:83], v[48:63]
	v_add_f32_e32 v182, v65, v64
	v_sub_f32_e32 v64, v69, v194
	v_sub_f32_e32 v68, v71, v194
	v_exp_f32_e32 v184, v68
	v_cvt_pk_bf16_f32 v68, v195, v84
	v_cvt_pk_bf16_f32 v69, v85, v86
	s_waitcnt lgkmcnt(1)
	v_mfma_f32_32x32x16_bf16 v[16:31], v[88:91], v[80:83], v[16:31]
	v_exp_f32_e32 v89, v64
	v_sub_f32_e32 v64, v70, v194
	v_exp_f32_e32 v183, v64
	ds_read_b128 v[64:67], v200 offset:34880
	v_add_f32_e32 v88, v198, v87
	v_cvt_pk_bf16_f32 v70, v87, v89
	v_cvt_pk_bf16_f32 v71, v183, v184
	v_mfma_f32_32x32x16_bf16 v[32:47], v[190:193], v[80:83], v[32:47]
	s_waitcnt lgkmcnt(0)
	v_mfma_f32_32x32x16_bf16 v[48:63], v[64:67], v[68:71], v[48:63]
	v_add3_u32 v208, s32, v179, v177
	s_waitcnt vmcnt(3)
	ds_write_b128 v208, v[100:103]
	v_add3_u32 v208, s32, v180, v177
	s_waitcnt vmcnt(2)
	ds_write_b128 v208, v[96:99]
	v_add3_u32 v208, s94, v176, v178
	s_waitcnt vmcnt(1)
	ds_write_b128 v208, v[104:107] offset:34816
	s_waitcnt vmcnt(0)
	ds_write_b128 v208, v[108:111] offset:44032
	s_mov_b32 s32, -1
	v_add_f32_e32 v64, v88, v182
	v_add_f32_e32 v65, v199, v89
	v_add_f32_e32 v182, v65, v64
	v_sub_f32_e32 v64, v72, v194
	v_exp_f32_e32 v185, v64
	v_sub_f32_e32 v72, v73, v194
	v_mfma_f32_32x32x16_bf16 v[0:15], v[186:189], v[80:83], v[0:15]
	ds_read_b128 v[80:83], v200 offset:39488
	ds_read_b128 v[84:87], v200 offset:34912
	ds_read_b128 v[64:67], v200 offset:44096
	ds_read_b128 v[88:91], v200 offset:39520
	v_exp_f32_e32 v186, v72
	v_sub_f32_e32 v72, v74, v194
	v_exp_f32_e32 v187, v72
	v_sub_f32_e32 v188, v75, v194
	v_exp_f32_e32 v188, v188
	s_waitcnt lgkmcnt(3)
	v_mfma_f32_32x32x16_bf16 v[32:47], v[80:83], v[68:71], v[32:47]
	ds_read_b128 v[72:75], v200 offset:48704
	ds_read_b128 v[80:83], v200 offset:44128
	s_waitcnt lgkmcnt(3)
	v_mfma_f32_32x32x16_bf16 v[16:31], v[64:67], v[68:71], v[16:31]
	v_sub_f32_e32 v64, v76, v194
	v_exp_f32_e32 v76, v64
	v_sub_f32_e32 v64, v77, v194
	v_exp_f32_e32 v77, v64
	ds_read_b128 v[64:67], v200 offset:48736
	s_waitcnt lgkmcnt(2)
	v_mfma_f32_32x32x16_bf16 v[0:15], v[72:75], v[68:71], v[0:15]
	v_sub_f32_e32 v68, v79, v194
	v_exp_f32_e32 v72, v78
	v_exp_f32_e32 v73, v68
	v_add_f32_e32 v74, v201, v183
	v_add_f32_e32 v74, v74, v182
	v_add_f32_e32 v75, v202, v184
	v_add_f32_e32 v74, v75, v74
	v_add_f32_e32 v75, v204, v185
	v_add_f32_e32 v74, v75, v74
	v_add_f32_e32 v75, v205, v186
	v_cvt_pk_bf16_f32 v68, v185, v186
	v_cvt_pk_bf16_f32 v69, v187, v188
	v_cvt_pk_bf16_f32 v70, v76, v77
	v_cvt_pk_bf16_f32 v71, v72, v73
	v_add_f32_e32 v74, v75, v74
	v_add_f32_e32 v75, v206, v187
	v_mfma_f32_32x32x16_bf16 v[48:63], v[84:87], v[68:71], v[48:63]
	v_add_f32_e32 v74, v75, v74
	v_add_f32_e32 v75, v207, v188
	v_add_f32_e32 v74, v75, v74
	v_add_f32_e32 v75, v92, v76
	v_add_f32_e32 v74, v75, v74
	v_add_f32_e32 v75, v93, v77
	v_add_f32_e32 v74, v75, v74
	v_mfma_f32_32x32x16_bf16 v[32:47], v[88:91], v[68:71], v[32:47]
	v_add_f32_e32 v72, v94, v72
	v_add_f32_e32 v72, v72, v74
	v_add_f32_e32 v73, v95, v73
	v_add_f32_e32 v72, v73, v72
	v_fmac_f32_e32 v72, v170, v154
	v_mov_b32_e32 v154, v181
	v_mov_b32_e32 v170, v72
	s_waitcnt lgkmcnt(1)
	v_mfma_f32_32x32x16_bf16 v[16:31], v[80:83], v[68:71], v[16:31]
	s_waitcnt lgkmcnt(0)
	v_mfma_f32_32x32x16_bf16 v[0:15], v[64:67], v[68:71], v[0:15]

.Lattn_u2_latedone:
	s_add_u32 s98, s98, 0x4000
	s_addc_u32 s99, s99, 0
	s_add_u32 s100, s100, 0x4000
	s_addc_u32 s101, s101, 0
	s_add_u32 s44, s44, 0x80
	s_addc_u32 s45, s45, 0
	s_add_u32 s46, s46, 0x80
	s_addc_u32 s47, s47, 0
	s_add_i32 s15, s15, 1
	s_cmp_eq_u32 s14, s15
	s_cbranch_scc1 .LBB0_1783
.LBB0_1772:
	s_and_b32 s0, s15, 1
	s_mul_i32 s1, s0, 0x4400
	s_add_i32 s17, s1, 0
	s_lshl_b32 s0, s0, 10
	s_add_i32 s16, s17, s0
	s_sub_i32 s32, 0x4400, s17
	s_sub_i32 s94, 0x400, s0
	s_add_i32 s94, s94, s32
	s_cmp_lg_u32 s15, 0
	s_cbranch_scc1 .Lattn_u2_nowrite
	v_add3_u32 v64, s17, v179, v177
	s_waitcnt vmcnt(3)
	ds_write_b128 v64, v[100:103]
	v_add3_u32 v64, s17, v180, v177
	s_waitcnt vmcnt(2)
	ds_write_b128 v64, v[96:99]
	v_add3_u32 v64, s16, v176, v178
	s_waitcnt vmcnt(1)
	ds_write_b128 v64, v[104:107] offset:34816
	s_waitcnt vmcnt(0)
	ds_write_b128 v64, v[108:111] offset:44032
.Lattn_u2_nowrite:
	v_lshl_add_u64 v[66:67], v[152:153], 0, s[98:99]
	v_lshl_add_u64 v[64:65], v[152:153], 0, s[100:101]
	s_waitcnt lgkmcnt(0)
	s_barrier
	global_load_dwordx4 v[100:103], v[66:67], off
	global_load_dwordx4 v[96:99], v[64:65], off
	v_lshl_add_u64 v[66:67], v[150:151], 0, s[44:45]
	s_lshr_b32 s0, s15, 2
	v_lshl_add_u64 v[64:65], v[150:151], 0, s[46:47]
	s_cmp_eq_u32 s0, s80
	global_load_dwordx4 v[104:107], v[66:67], off offset:128
	global_load_dwordx4 v[108:111], v[64:65], off offset:128
	s_cselect_b64 s[8:9], -1, 0
	s_lshl_b32 s1, 1, s0
	v_and_b32_e32 v64, s1, v172
	s_cmp_lg_u32 s0, s80
	v_cmp_ne_u32_e64 s[0:1], 0, v64
	s_mov_b64 s[4:5], -1
	s_cbranch_scc0 .LBB0_1775
	v_cndmask_b32_e64 v64, 0, 1, s[0:1]
	v_cmp_ne_u32_e32 vcc, 0, v64
	s_cmp_lg_u64 vcc, 0
	s_cselect_b64 s[10:11], -1, 0
	s_and_b32 s18, s15, 3
	s_cbranch_execz .LBB0_1776

.LBB0_1783:
	s_and_b32 s0, s14, 1
	s_mul_i32 s1, s0, 0x4400
	s_add_i32 s15, s1, 0
	s_lshl_b32 s0, s0, 10
	s_add_i32 s12, s15, s0
	s_lshr_b32 s0, s14, 2
	s_cmp_eq_u32 s0, s80
	v_lshrrev_b32_e32 v64, s0, v172
	s_cselect_b64 s[8:9], -1, 0
	v_and_b32_e32 v64, 1, v64
	v_cmp_eq_u32_e64 s[0:1], 1, v64
	s_mov_b64 s[4:5], -1
	s_and_b64 vcc, exec, s[8:9]
	s_waitcnt lgkmcnt(0)
	s_barrier
	s_cbranch_vccnz .LBB0_1786
	v_cndmask_b32_e64 v64, 0, 1, s[0:1]
	v_cmp_ne_u32_e32 vcc, 0, v64
	s_cmp_lg_u64 vcc, 0
	s_cselect_b64 s[10:11], -1, 0
	s_and_b32 s13, s14, 3
	s_cbranch_execz .LBB0_1787
